# prep x->bf16 row loop and final rmsnorm row loop: all loads of a row issued at once (were 4 serialized round trips per row)
# baseline (speedup 1.0000x reference)
.LBB0_23:
	s_waitcnt lgkmcnt(0)
	global_load_dwordx4 v[12:15], v10, s[28:29]
	global_load_dwordx4 v[28:31], v10, s[28:29] offset:1024
	global_load_dwordx4 v[32:35], v10, s[28:29] offset:2048
	global_load_dwordx4 v[36:39], v10, s[28:29] offset:3072
	s_waitcnt vmcnt(3)
	v_cvt_pk_bf16_f32 v40, v12, v13
	v_cvt_pk_bf16_f32 v41, v14, v15
	global_store_dwordx2 v11, v[40:41], s[24:25]
	v_lshlrev_b32_e32 v48, 16, v40
	v_and_b32_e32 v49, 0xffff0000, v40
	v_lshlrev_b32_e32 v50, 16, v41
	v_and_b32_e32 v51, 0xffff0000, v41
	v_mul_f32_e32 v49, v49, v49
	v_mul_f32_e32 v51, v51, v51
	v_fmac_f32_e32 v49, v48, v48
	v_fmac_f32_e32 v51, v50, v50
	v_add_f32_e32 v52, v49, v51
	s_waitcnt vmcnt(3)
	v_cvt_pk_bf16_f32 v42, v28, v29
	v_cvt_pk_bf16_f32 v43, v30, v31
	global_store_dwordx2 v11, v[42:43], s[24:25] offset:512
	v_lshlrev_b32_e32 v48, 16, v42
	v_and_b32_e32 v49, 0xffff0000, v42
	v_lshlrev_b32_e32 v50, 16, v43
	v_and_b32_e32 v51, 0xffff0000, v43
	v_mul_f32_e32 v49, v49, v49
	v_mul_f32_e32 v51, v51, v51
	v_fmac_f32_e32 v49, v48, v48
	v_fmac_f32_e32 v51, v50, v50
	v_add_f32_e32 v49, v49, v51
	v_add_f32_e32 v52, v52, v49
	s_waitcnt vmcnt(3)
	v_cvt_pk_bf16_f32 v44, v32, v33
	v_cvt_pk_bf16_f32 v45, v34, v35
	global_store_dwordx2 v11, v[44:45], s[24:25] offset:1024
	v_lshlrev_b32_e32 v48, 16, v44
	v_and_b32_e32 v49, 0xffff0000, v44
	v_lshlrev_b32_e32 v50, 16, v45
	v_and_b32_e32 v51, 0xffff0000, v45
	v_mul_f32_e32 v49, v49, v49
	v_mul_f32_e32 v51, v51, v51
	v_fmac_f32_e32 v49, v48, v48
	v_fmac_f32_e32 v51, v50, v50
	v_add_f32_e32 v49, v49, v51
	v_add_f32_e32 v52, v52, v49
	s_waitcnt vmcnt(3)
	v_cvt_pk_bf16_f32 v46, v36, v37
	v_cvt_pk_bf16_f32 v47, v38, v39
	global_store_dwordx2 v11, v[46:47], s[24:25] offset:1536
	v_lshlrev_b32_e32 v48, 16, v46
	v_and_b32_e32 v49, 0xffff0000, v46
	v_lshlrev_b32_e32 v50, 16, v47
	v_and_b32_e32 v51, 0xffff0000, v47
	v_mul_f32_e32 v49, v49, v49
	v_mul_f32_e32 v51, v51, v51
	v_fmac_f32_e32 v49, v48, v48
	v_fmac_f32_e32 v51, v50, v50
	v_add_f32_e32 v49, v49, v51
	v_add_f32_e32 v52, v52, v49
	v_mov_b32_e32 v12, v52
	ds_bpermute_b32 v13, v4, v12
	s_waitcnt lgkmcnt(0)
	v_add_f32_e32 v12, v12, v13
	ds_bpermute_b32 v13, v5, v12
	s_waitcnt lgkmcnt(0)
	v_add_f32_e32 v12, v12, v13
	ds_bpermute_b32 v13, v6, v12
	s_waitcnt lgkmcnt(0)
	v_add_f32_e32 v12, v12, v13
	ds_bpermute_b32 v13, v7, v12
	s_waitcnt lgkmcnt(0)
	v_add_f32_e32 v12, v12, v13
	ds_bpermute_b32 v13, v8, v12
	s_waitcnt lgkmcnt(0)
	v_add_f32_e32 v12, v12, v13
	ds_bpermute_b32 v13, v9, v12
	s_and_saveexec_b64 s[34:35], s[6:7]
	s_cbranch_execz .LBB0_22
	s_waitcnt lgkmcnt(0)
	v_add_f32_e32 v12, v12, v13
	v_cndmask_b32_e32 v12, 0, v12, vcc
	global_store_dword v[2:3], v12, off
	s_branch .LBB0_22

.LBB0_2130:
	v_mov_b32_e32 v18, s10
	global_load_dwordx4 v[6:9], v1, s[10:11] offset:-32
	global_load_dwordx4 v[10:13], v1, s[10:11] offset:-16
	global_load_dwordx4 v[14:17], v1, s[10:11]
	v_mov_b32_e32 v19, s11
	v_add_co_u32_e32 v28, vcc, 0xffffffd0, v18
	global_load_dwordx2 v[26:27], v5, s[6:7]
	s_nop 0
	v_addc_co_u32_e32 v29, vcc, -1, v19, vcc
	flat_load_dwordx4 v[18:21], v[28:29]
	global_load_dwordx4 v[22:25], v[2:3], off
	global_load_dwordx2 v[30:31], v5, s[6:7] offset:512
	global_load_dwordx2 v[32:33], v5, s[6:7] offset:1024
	global_load_dwordx2 v[34:35], v5, s[6:7] offset:1536
	global_load_dwordx4 v[36:39], v[2:3], off offset:1024
	global_load_dwordx4 v[40:43], v[2:3], off offset:2048
	global_load_dwordx4 v[44:47], v[2:3], off offset:3072
	s_add_i32 s2, s2, s66
	s_waitcnt vmcnt(0)
	v_mov_b32_e32 v28, v7
	v_mov_b32_e32 v29, v8
	v_mov_b32_e32 v7, v9
	v_add_f32_e32 v8, v10, v11
	v_add_f32_e32 v10, v12, v13
	v_mov_b32_e32 v9, v16
	v_mov_b32_e32 v11, v17
	v_pk_add_f32 v[8:9], v[8:9], v[10:11]
	s_waitcnt lgkmcnt(0)
	v_mov_b32_e32 v10, v19
	v_mov_b32_e32 v11, v20
	v_mov_b32_e32 v19, v21
	v_pk_add_f32 v[6:7], v[28:29], v[6:7]
	v_pk_add_f32 v[10:11], v[10:11], v[18:19]
	v_pk_add_f32 v[6:7], v[6:7], v[6:7] op_sel:[0,1] op_sel_hi:[1,0]
	v_pk_add_f32 v[10:11], v[10:11], v[10:11] op_sel:[0,1] op_sel_hi:[1,0]
	v_mov_b32_e32 v7, v15
	v_mov_b32_e32 v11, v14
	v_pk_add_f32 v[6:7], v[10:11], v[6:7]
	v_lshlrev_b32_e32 v12, 16, v26
	v_pk_add_f32 v[6:7], v[6:7], v[8:9]
	v_and_b32_e32 v13, 0xffff0000, v26
	v_add_f32_e32 v6, v6, v7
	v_fmamk_f32 v6, v6, 0x3a800000, v0
	v_mul_f32_e32 v7, 0x4b800000, v6
	v_cmp_gt_f32_e32 vcc, s3, v6
	v_lshlrev_b32_e32 v16, 16, v27
	v_and_b32_e32 v17, 0xffff0000, v27
	v_cndmask_b32_e32 v6, v6, v7, vcc
	v_rsq_f32_e32 v6, v6
	s_nop 0
	v_mul_f32_e32 v7, 0x45800000, v6
	v_cndmask_b32_e32 v10, v6, v7, vcc
	v_pk_mul_f32 v[6:7], v[10:11], v[12:13] op_sel_hi:[0,1]
	v_pk_mul_f32 v[8:9], v[10:11], v[16:17] op_sel_hi:[0,1]
	v_pk_mul_f32 v[8:9], v[24:25], v[8:9]
	v_pk_mul_f32 v[6:7], v[22:23], v[6:7]
	global_store_dwordx4 v4, v[6:9], s[0:1]
	v_mov_b32_e32 v12, v30
	v_mov_b32_e32 v13, v31
	s_nop 0
	v_mov_b32_e32 v6, v36
	v_mov_b32_e32 v7, v37
	v_mov_b32_e32 v8, v38
	v_mov_b32_e32 v9, v39
	v_lshlrev_b32_e32 v14, 16, v12
	v_and_b32_e32 v15, 0xffff0000, v12
	v_lshlrev_b32_e32 v12, 16, v13
	v_and_b32_e32 v13, 0xffff0000, v13
	v_pk_mul_f32 v[14:15], v[10:11], v[14:15] op_sel_hi:[0,1]
	v_pk_mul_f32 v[12:13], v[10:11], v[12:13] op_sel_hi:[0,1]
	v_pk_mul_f32 v[8:9], v[8:9], v[12:13]
	v_pk_mul_f32 v[6:7], v[6:7], v[14:15]
	global_store_dwordx4 v4, v[6:9], s[0:1] offset:1024
	v_mov_b32_e32 v12, v32
	v_mov_b32_e32 v13, v33
	s_nop 0
	v_mov_b32_e32 v6, v40
	v_mov_b32_e32 v7, v41
	v_mov_b32_e32 v8, v42
	v_mov_b32_e32 v9, v43
	v_lshlrev_b32_e32 v14, 16, v12
	v_and_b32_e32 v15, 0xffff0000, v12
	v_lshlrev_b32_e32 v12, 16, v13
	v_and_b32_e32 v13, 0xffff0000, v13
	v_pk_mul_f32 v[14:15], v[10:11], v[14:15] op_sel_hi:[0,1]
	v_pk_mul_f32 v[12:13], v[10:11], v[12:13] op_sel_hi:[0,1]
	v_pk_mul_f32 v[8:9], v[8:9], v[12:13]
	v_pk_mul_f32 v[6:7], v[6:7], v[14:15]
	global_store_dwordx4 v4, v[6:9], s[0:1] offset:2048
	v_mov_b32_e32 v12, v34
	v_mov_b32_e32 v13, v35
	s_nop 0
	v_mov_b32_e32 v6, v44
	v_mov_b32_e32 v7, v45
	v_mov_b32_e32 v8, v46
	v_mov_b32_e32 v9, v47
	v_lshlrev_b32_e32 v14, 16, v12
	v_and_b32_e32 v15, 0xffff0000, v12
	v_lshlrev_b32_e32 v12, 16, v13
	v_and_b32_e32 v13, 0xffff0000, v13
	v_pk_mul_f32 v[14:15], v[10:11], v[14:15] op_sel_hi:[0,1]
	v_pk_mul_f32 v[10:11], v[10:11], v[12:13] op_sel_hi:[0,1]
	v_pk_mul_f32 v[8:9], v[8:9], v[10:11]
	v_pk_mul_f32 v[6:7], v[6:7], v[14:15]
	global_store_dwordx4 v4, v[6:9], s[0:1] offset:3072
	s_add_u32 s0, s0, s4
	s_addc_u32 s1, s1, s5
	s_add_u32 s6, s6, s8
	s_addc_u32 s7, s7, s9
	s_add_u32 s10, s10, s12
	s_addc_u32 s11, s11, s13
	s_cmpk_lt_i32 s2, 0x4000
	s_cbranch_scc1 .LBB0_2130
